# same as previous plus scan loop shifted by one s_nop (code placement check)
# baseline (speedup 1.0000x reference)
; DEVI int ltid() { int t = __builtin_amdgcn_workitem_id_x(); asm volatile("" : "+v"(t)); return t; }
; __device__ void scan_block(const Params& P, int sb, unsigned char* lds) {
;     ...
;   const int head = sb >> 2, rg = sb & 3, tid = ltid();
;   const bool loader = tid >= 256; const int lt = tid - 256;
;   const int lane = tid & 63, wv = (tid >> 6) & 3, ks = lane & 15, myrow = wv * 4 + (lane >> 4);
;   f32x4 S = {0.f, 0.f, 0.f, 0.f};
;   const int hb = head * 64;
;     ...
;     for (int c = 0; c < NCH; ++c) {
;       const float* b = buf + (c & 1) * SC_STAGE;
;       const float* q = b + ks * 4;
;       const float* qv = b + 320 + myrow;
;       float* yo = Y + (size_t)(c * SC_CH + ks) * 1024 + hb + rg * 16 + myrow;
;       f32x4 w4 = *(const f32x4*)(q), k4 = *(const f32x4*)(q + 64), b4 = *(const f32x4*)(q + 128), kh4 = *(const f32x4*)(q + 192), r4 = *(const f32x4*)(q + 256);
;       float v = qv[0];
.LBB0_50:
	s_andn2_b64 vcc, exec, s[8:9]
	v_readlane_b32 s3, v252, 9
	s_cbranch_vccnz .LBB0_150
	v_readlane_b32 s2, v252, 0
	v_mov_b32_e32 v149, v169
	s_movk_i32 s0, 0x100
	s_nop 0
	v_cmp_gt_i32_e32 vcc, s0, v149
	s_lshl_b32 s0, s2, 4
	s_and_b32 s12, s0, 0xffffffc0
	s_barrier
	s_and_saveexec_b64 s[0:1], vcc
	s_xor_b64 s[82:83], exec, s[0:1]
	s_cbranch_execz .LBB0_55
	s_mov_b64 s[90:91], s[62:63]
	v_bfe_u32 v8, v149, 4, 4
	v_and_b32_e32 v0, 15, v149
	s_setprio 2
	s_ashr_i32 s13, s12, 31
	s_and_b32 s6, s2, 3
	s_lshl_b32 s8, s6, 6
	s_lshl_b64 s[6:7], s[12:13], 2
	s_add_u32 s6, s6, s8
	s_addc_u32 s7, s7, 0
	v_readlane_b32 s4, v251, 36
	v_readlane_b32 s5, v251, 37
	v_and_b32_e32 v2, 2, v0
	v_and_b32_e32 v3, 1, v0
	s_add_u32 s4, s4, s6
	s_addc_u32 s5, s5, s7
	v_cmp_ne_u32_e64 s[40:41], 0, v2
	v_cmp_ne_u32_e64 s[42:43], 0, v3
	v_lshl_add_u32 v9, v0, 4, 16
	v_lshl_add_u32 v10, v8, 2, 16
	v_bfrev_b32_e32 v2, v0
	v_lshrrev_b32_e32 v2, 16, v2
	v_lshl_add_u32 v2, v8, 2, v2
	v_add_u32_e32 v3, 0x10000, v2
	v_mov_b32_e32 v4, 0
	v_mov_b32_e32 v5, 0
	v_mov_b32_e32 v6, 0
	v_mov_b32_e32 v7, 0
	s_mov_b32 s3, 0
	s_waitcnt vmcnt(0)
	s_barrier
	ds_read_b128 v[12:15], v9 offset:256
	ds_read_b128 v[16:19], v9 offset:0
	ds_read_b128 v[20:23], v9 offset:768
	ds_read_b32 v24, v10 offset:1280
	ds_read_b128 v[44:47], v9 offset:512
	ds_read_b128 v[36:39], v9 offset:1024
	ds_read_b128 v[60:63], v9 offset:1600
	ds_read_b128 v[64:67], v9 offset:1344
	ds_read_b128 v[28:31], v9 offset:2112
	ds_read_b32 v32, v10 offset:2624
	ds_read_b128 v[48:51], v9 offset:1856
	s_nop 0
